# v60 + softmax: packed add -> two scalar adds, l update as one fma, two blind pads removed
# speedup vs baseline: 1.0082x; 1.0082x over previous
; __device__ __forceinline__ bool softmax_pp(f32x16& p0, f32x16& p1, float& m_reg, float& l_reg, f32x16& negm, float& alpha, float& m_run, float dq, float nslope,
;                                            bf16x8& pa0, bf16x8& pa1, bf16x8& pa2, bf16x8& pa3) {
;     ...
;   float a = fmaxf(fmaxf(p0[0], p0[1]), p1[0]), bq = fmaxf(fmaxf(p0[2], p0[3]), p1[1]); a = fmaxf(fmaxf(a, p1[2]), p1[3]);
; #pragma unroll
;   for (int r = 4; r < 16; r += 4) { a = fmaxf(fmaxf(a, p0[r]), p0[r + 1]); bq = fmaxf(fmaxf(bq, p0[r + 2]), p0[r + 3]); a = fmaxf(fmaxf(a, p1[r]), p1[r + 1]); bq = fmaxf(fmaxf(bq, p1[r + 2]), p1[r + 3]); }
;   float pmax = fmaxf(a, bq);
;   { auto rr = __builtin_amdgcn_permlane32_swap(__float_as_uint(pmax), __float_as_uint(pmax), false, false);
;     pmax = fmaxf(__uint_as_float(rr[0]), __uint_as_float(rr[1])); }
;   alpha = 1.f;
;   { const float tmax = pmax + m_reg;
;     if (__all(tmax < m_run - TSKIP)) return false;
;     m_run = fmaxf(m_run, tmax); }
;   if (__builtin_expect(!__all(pmax <= THRL), 0)) { const float dl = fmaxf(pmax, 0.f); m_reg += dl; alpha = __builtin_amdgcn_exp2f(-dl);
; #pragma unroll
;     for (int r = 0; r < 16; ++r) { p0[r] -= dl; p1[r] -= dl; }
; #pragma unroll
;     for (int r = 0; r < 16; ++r) negm[r] = -m_reg; }
; #pragma unroll
;   for (int r = 0; r < 16; ++r) { p0[r] = __builtin_amdgcn_exp2f(p0[r]); p1[r] = __builtin_amdgcn_exp2f(p1[r]); }
;   float ps = 0;
; #pragma unroll
;   for (int r = 0; r < 16; ++r) ps += p0[r];
; #pragma unroll
;   for (int r = 0; r < 16; ++r) ps += p1[r];
;   { auto rr = __builtin_amdgcn_permlane32_swap(__float_as_uint(ps), __float_as_uint(ps), false, false);
;     ps = __uint_as_float(rr[0]) + __uint_as_float(rr[1]); }
;   l_reg = l_reg * alpha + ps;
;     ...
;   PK4(p0, 0, pa0); PK4(p0, 8, pa1); PK4(p1, 0, pa2); PK4(p1, 8, pa3);
.Lafter_bias_0:
	v_max_f32_e32 v0, v98, v99
	v_max3_f32 v14, v100, v101, v115
	v_max3_f32 v0, v0, v114, v116
	v_max3_f32 v0, v0, v117, v102
	v_max3_f32 v14, v14, v104, v105
	v_max3_f32 v0, v0, v103, v118
	v_max3_f32 v14, v14, v120, v121
	v_max3_f32 v0, v0, v119, v106
	v_max3_f32 v14, v14, v108, v109
	v_max3_f32 v0, v0, v107, v122
	v_max3_f32 v14, v14, v124, v125
	v_max3_f32 v0, v0, v123, v110
	v_max3_f32 v14, v14, v112, v113
	v_max3_f32 v0, v0, v111, v126
	v_max3_f32 v14, v14, v128, v129
	v_max3_f32 v0, v0, v127, v14
	v_mov_b32_e32 v14, v0
	s_nop 1
	v_permlane32_swap_b32_e32 v0, v14
	v_max_f32_e32 v167, v0, v14
	v_add_f32_e32 v14, v172, v166
	v_add_f32_e32 v15, v173, v167
	v_cmp_lt_f32_e32 vcc, v15, v14
	s_cmp_lg_u64 vcc, exec
	s_cselect_b64 s[14:15], -1, 0
	s_cmp_eq_u64 vcc, exec
	s_cbranch_scc1 .LBB0_370
	v_cmp_ge_f32_e32 vcc, s59, v167
	s_cmp_eq_u64 vcc, exec
	s_cbranch_scc0 .LBB0_395
	v_mov_b32_e32 v0, 1.0
.LBB0_369:
	v_max_f32_e32 v172, v172, v15
	v_exp_f32_e32 v2, v98
	v_exp_f32_e32 v3, v99
	v_exp_f32_e32 v4, v100
	v_exp_f32_e32 v5, v101
	v_exp_f32_e32 v12, v116
	v_exp_f32_e32 v6, v102
	v_exp_f32_e32 v7, v103
	v_add_f32_e32 v116, v3, v2
	v_exp_f32_e32 v8, v104
	v_add_f32_e32 v116, v4, v116
	v_exp_f32_e32 v9, v105
	v_add_f32_e32 v116, v5, v116
	v_exp_f32_e32 v100, v106
	v_add_f32_e32 v116, v6, v116
	v_exp_f32_e32 v102, v107
	v_add_f32_e32 v116, v7, v116
	v_exp_f32_e32 v104, v108
	v_add_f32_e32 v116, v8, v116
	v_exp_f32_e32 v106, v109
	v_add_f32_e32 v116, v9, v116
	v_exp_f32_e32 v108, v110
	v_add_f32_e32 v116, v100, v116
	v_exp_f32_e32 v110, v111
	v_add_f32_e32 v116, v102, v116
	v_exp_f32_e32 v112, v112
	v_add_f32_e32 v116, v104, v116
	v_exp_f32_e32 v113, v113
	v_add_f32_e32 v116, v106, v116
	v_exp_f32_e32 v10, v114
	v_add_f32_e32 v116, v108, v116
	v_exp_f32_e32 v11, v115
	v_add_f32_e32 v116, v110, v116
	v_add_f32_e32 v116, v112, v116
	v_exp_f32_e32 v13, v117
	v_add_f32_e32 v116, v113, v116
	v_exp_f32_e32 v14, v118
	v_add_f32_e32 v116, v10, v116
	v_exp_f32_e32 v15, v119
	v_add_f32_e32 v116, v11, v116
	v_exp_f32_e32 v98, v120
	v_add_f32_e32 v116, v12, v116
	v_exp_f32_e32 v99, v121
	v_add_f32_e32 v116, v13, v116
	v_exp_f32_e32 v101, v122
	v_add_f32_e32 v116, v14, v116
	v_exp_f32_e32 v103, v123
	v_add_f32_e32 v116, v15, v116
	v_exp_f32_e32 v105, v124
	v_add_f32_e32 v116, v98, v116
	v_exp_f32_e32 v107, v125
	v_add_f32_e32 v116, v99, v116
	v_exp_f32_e32 v109, v126
	v_add_f32_e32 v116, v101, v116
	v_exp_f32_e32 v111, v127
	v_add_f32_e32 v116, v103, v116
	v_exp_f32_e32 v114, v128
	v_add_f32_e32 v116, v105, v116
	v_exp_f32_e32 v115, v129
	v_add_f32_e32 v116, v107, v116
	v_add_f32_e32 v116, v109, v116
	v_add_f32_e32 v116, v111, v116
	v_add_f32_e32 v116, v114, v116
	v_add_f32_e32 v116, v115, v116
	v_mov_b32_e32 v117, v116
	s_nop 1
	v_permlane32_swap_b32_e32 v116, v117
	v_add_f32_e32 v116, v116, v117
	v_cvt_pk_bf16_f32 v2, v2, v3
	v_cvt_pk_bf16_f32 v3, v4, v5
	v_cvt_pk_bf16_f32 v4, v6, v7
	v_cvt_pk_bf16_f32 v5, v8, v9
	v_cvt_pk_bf16_f32 v6, v100, v102
	v_cvt_pk_bf16_f32 v7, v104, v106
	v_cvt_pk_bf16_f32 v8, v108, v110
	v_cvt_pk_bf16_f32 v9, v112, v113
	v_cvt_pk_bf16_f32 v10, v10, v11
	v_cvt_pk_bf16_f32 v11, v12, v13
	v_cvt_pk_bf16_f32 v12, v14, v15
	v_cvt_pk_bf16_f32 v13, v98, v99
	v_cvt_pk_bf16_f32 v162, v101, v103
	v_cvt_pk_bf16_f32 v163, v105, v107
	v_cvt_pk_bf16_f32 v164, v109, v111
	v_cvt_pk_bf16_f32 v165, v114, v115
	v_permlane32_swap_b32_e32 v2, v4
	v_permlane32_swap_b32_e32 v3, v5
	v_permlane32_swap_b32_e32 v6, v8
	v_permlane32_swap_b32_e32 v7, v9
	v_permlane32_swap_b32_e32 v10, v12
	v_permlane32_swap_b32_e32 v11, v13
	v_permlane32_swap_b32_e32 v162, v164
	v_permlane32_swap_b32_e32 v163, v165
	v_fma_f32 v80, v80, v0, v116
	s_branch .LBB0_371

; __device__ __forceinline__ bool softmax_pp(f32x16& p0, f32x16& p1, float& m_reg, float& l_reg, f32x16& negm, float& alpha, float& m_run, float dq, float nslope,
;                                            bf16x8& pa0, bf16x8& pa1, bf16x8& pa2, bf16x8& pa3) {
;     ...
;   float a = fmaxf(fmaxf(p0[0], p0[1]), p1[0]), bq = fmaxf(fmaxf(p0[2], p0[3]), p1[1]); a = fmaxf(fmaxf(a, p1[2]), p1[3]);
; #pragma unroll
;   for (int r = 4; r < 16; r += 4) { a = fmaxf(fmaxf(a, p0[r]), p0[r + 1]); bq = fmaxf(fmaxf(bq, p0[r + 2]), p0[r + 3]); a = fmaxf(fmaxf(a, p1[r]), p1[r + 1]); bq = fmaxf(fmaxf(bq, p1[r + 2]), p1[r + 3]); }
;   float pmax = fmaxf(a, bq);
;   { auto rr = __builtin_amdgcn_permlane32_swap(__float_as_uint(pmax), __float_as_uint(pmax), false, false);
;     pmax = fmaxf(__uint_as_float(rr[0]), __uint_as_float(rr[1])); }
;   alpha = 1.f;
;   { const float tmax = pmax + m_reg;
;     if (__all(tmax < m_run - TSKIP)) return false;
;     m_run = fmaxf(m_run, tmax); }
;   if (__builtin_expect(!__all(pmax <= THRL), 0)) { const float dl = fmaxf(pmax, 0.f); m_reg += dl; alpha = __builtin_amdgcn_exp2f(-dl);
; #pragma unroll
;     for (int r = 0; r < 16; ++r) { p0[r] -= dl; p1[r] -= dl; }
; #pragma unroll
;     for (int r = 0; r < 16; ++r) negm[r] = -m_reg; }
; #pragma unroll
;   for (int r = 0; r < 16; ++r) { p0[r] = __builtin_amdgcn_exp2f(p0[r]); p1[r] = __builtin_amdgcn_exp2f(p1[r]); }
;   float ps = 0;
; #pragma unroll
;   for (int r = 0; r < 16; ++r) ps += p0[r];
; #pragma unroll
;   for (int r = 0; r < 16; ++r) ps += p1[r];
;   { auto rr = __builtin_amdgcn_permlane32_swap(__float_as_uint(ps), __float_as_uint(ps), false, false);
;     ps = __uint_as_float(rr[0]) + __uint_as_float(rr[1]); }
;   l_reg = l_reg * alpha + ps;
;     ...
;   PK4(p0, 0, pa0); PK4(p0, 8, pa1); PK4(p1, 0, pa2); PK4(p1, 8, pa3);
.Lafter_bias_1:
	v_max_f32_e32 v0, v98, v99
	v_max3_f32 v14, v100, v101, v115
	v_max3_f32 v0, v0, v114, v116
	v_max3_f32 v0, v0, v117, v102
	v_max3_f32 v14, v14, v104, v105
	v_max3_f32 v0, v0, v103, v118
	v_max3_f32 v14, v14, v120, v121
	v_max3_f32 v0, v0, v119, v106
	v_max3_f32 v14, v14, v108, v109
	v_max3_f32 v0, v0, v107, v122
	v_max3_f32 v14, v14, v124, v125
	v_max3_f32 v0, v0, v123, v110
	v_max3_f32 v14, v14, v112, v113
	v_max3_f32 v0, v0, v111, v126
	v_max3_f32 v14, v14, v128, v129
	v_max3_f32 v0, v0, v127, v14
	v_mov_b32_e32 v14, v0
	s_nop 1
	v_permlane32_swap_b32_e32 v0, v14
	v_max_f32_e32 v167, v0, v14
	v_add_f32_e32 v14, v172, v166
	v_add_f32_e32 v15, v173, v167
	v_mov_b32_e32 v0, 1.0
	v_cmp_lt_f32_e32 vcc, v15, v14
	s_cmp_lg_u64 vcc, exec
	s_cselect_b64 s[14:15], -1, 0
	s_cmp_eq_u64 vcc, exec
	s_cbranch_scc1 .LBB0_385
	v_cmp_ge_f32_e32 vcc, s59, v167
	s_cmp_eq_u64 vcc, exec
	s_cbranch_scc0 .LBB0_396
	v_mov_b32_e32 v0, 1.0
.LBB0_384:
	v_max_f32_e32 v172, v172, v15
	v_exp_f32_e32 v2, v98
	v_exp_f32_e32 v3, v99
	v_exp_f32_e32 v4, v100
	v_exp_f32_e32 v5, v101
	v_exp_f32_e32 v12, v116
	v_exp_f32_e32 v6, v102
	v_exp_f32_e32 v7, v103
	v_add_f32_e32 v116, v3, v2
	v_exp_f32_e32 v8, v104
	v_add_f32_e32 v116, v4, v116
	v_exp_f32_e32 v9, v105
	v_add_f32_e32 v116, v5, v116
	v_exp_f32_e32 v100, v106
	v_add_f32_e32 v116, v6, v116
	v_exp_f32_e32 v102, v107
	v_add_f32_e32 v116, v7, v116
	v_exp_f32_e32 v104, v108
	v_add_f32_e32 v116, v8, v116
	v_exp_f32_e32 v106, v109
	v_add_f32_e32 v116, v9, v116
	v_exp_f32_e32 v108, v110
	v_add_f32_e32 v116, v100, v116
	v_exp_f32_e32 v110, v111
	v_add_f32_e32 v116, v102, v116
	v_exp_f32_e32 v112, v112
	v_add_f32_e32 v116, v104, v116
	v_exp_f32_e32 v113, v113
	v_add_f32_e32 v116, v106, v116
	v_exp_f32_e32 v10, v114
	v_add_f32_e32 v116, v108, v116
	v_exp_f32_e32 v11, v115
	v_add_f32_e32 v116, v110, v116
	v_add_f32_e32 v116, v112, v116
	v_exp_f32_e32 v13, v117
	v_add_f32_e32 v116, v113, v116
	v_exp_f32_e32 v14, v118
	v_add_f32_e32 v116, v10, v116
	v_exp_f32_e32 v15, v119
	v_add_f32_e32 v116, v11, v116
	v_exp_f32_e32 v98, v120
	v_add_f32_e32 v116, v12, v116
	v_exp_f32_e32 v99, v121
	v_add_f32_e32 v116, v13, v116
	v_exp_f32_e32 v101, v122
	v_add_f32_e32 v116, v14, v116
	v_exp_f32_e32 v103, v123
	v_add_f32_e32 v116, v15, v116
	v_exp_f32_e32 v105, v124
	v_add_f32_e32 v116, v98, v116
	v_exp_f32_e32 v107, v125
	v_add_f32_e32 v116, v99, v116
	v_exp_f32_e32 v109, v126
	v_add_f32_e32 v116, v101, v116
	v_exp_f32_e32 v111, v127
	v_add_f32_e32 v116, v103, v116
	v_exp_f32_e32 v114, v128
	v_add_f32_e32 v116, v105, v116
	v_exp_f32_e32 v115, v129
	v_add_f32_e32 v116, v107, v116
	v_add_f32_e32 v116, v109, v116
	v_add_f32_e32 v116, v111, v116
	v_add_f32_e32 v116, v114, v116
	v_add_f32_e32 v116, v115, v116
	v_mov_b32_e32 v117, v116
	s_nop 1
	v_permlane32_swap_b32_e32 v116, v117
	v_add_f32_e32 v116, v116, v117
	v_cvt_pk_bf16_f32 v2, v2, v3
	v_cvt_pk_bf16_f32 v3, v4, v5
	v_cvt_pk_bf16_f32 v4, v6, v7
	v_cvt_pk_bf16_f32 v5, v8, v9
	v_cvt_pk_bf16_f32 v6, v100, v102
	v_cvt_pk_bf16_f32 v7, v104, v106
	v_cvt_pk_bf16_f32 v8, v108, v110
	v_cvt_pk_bf16_f32 v9, v112, v113
	v_cvt_pk_bf16_f32 v10, v10, v11
	v_cvt_pk_bf16_f32 v11, v12, v13
	v_cvt_pk_bf16_f32 v12, v14, v15
	v_cvt_pk_bf16_f32 v13, v98, v99
	v_cvt_pk_bf16_f32 v162, v101, v103
	v_cvt_pk_bf16_f32 v163, v105, v107
	v_cvt_pk_bf16_f32 v164, v109, v111
	v_cvt_pk_bf16_f32 v165, v114, v115
	v_permlane32_swap_b32_e32 v2, v4
	v_permlane32_swap_b32_e32 v3, v5
	v_permlane32_swap_b32_e32 v6, v8
	v_permlane32_swap_b32_e32 v7, v9
	v_permlane32_swap_b32_e32 v10, v12
	v_permlane32_swap_b32_e32 v11, v13
	v_permlane32_swap_b32_e32 v162, v164
	v_permlane32_swap_b32_e32 v163, v165
	v_fma_f32 v80, v80, v0, v116
